# remove redundant buffer_wbl2 after act_fixup; hoist zero-init to drop 6 conservative vmcnt(0) in act_fixup load phase
# speedup vs baseline: 1.0171x; 1.0171x over previous
; __device__ __forceinline__ void act_fixup(const Params& p, int l, int pm) {
;     ...
;     constexpr int NU = 8 * (DFF / 8), NK = (NU + 511) / 512;
;     u32x4 rg[NK], ru[NK], r1[NK], r2[NK];
; #pragma unroll
;     for (int k = 0; k < NK; ++k) {
;         const int idx = tid + 512 * k;
;         rg[k] = ru[k] = r1[k] = r2[k] = (u32x4){0u, 0u, 0u, 0u};
;         if (idx < NU) {
;             const int rsel = idx / (DFF / 8), c0 = (idx % (DFF / 8)) * 8, blk = pm * 4 + (rsel >> 1), rr = rsel & 1;
;             const bool seq0 = (blk & 31) == 0;
;             rg[k] = *(const u32x4*)(gs01 + ((size_t)blk * 2 + rr) * DFF + c0);
;             ru[k] = *(const u32x4*)(us01 + ((size_t)blk * 2 + rr) * DFF + c0);
;             if (rr == 0) { if (!seq0) { r1[k] = *(const u32x4*)(gs23 + ((size_t)(blk - 1) * 2 + 1) * DFF + c0); r2[k] = *(const u32x4*)(gs23 + ((size_t)(blk - 1) * 2 + 0) * DFF + c0); } }
.LBB0_65:
	v_mov_b32_e32 v102, v163
	s_movk_i32 s0, 0xb00
	s_waitcnt vmcnt(0)
	v_mov_b32_e32 v58, v1
	v_cmp_gt_i32_e64 s[50:51], s0, v102
	v_mov_b32_e32 v59, v1
	s_mov_b32 s0, 0x2e8ba2e9
	v_mov_b32_e32 v56, v1
	v_mov_b32_e32 v57, v1
	v_mul_hi_i32 v0, v102, s0
	v_mov_b64_e32 v[78:79], v[58:59]
	s_lshl_b32 s30, s26, 2
	v_mov_b32_e32 v48, 0
	v_lshrrev_b32_e32 v103, 31, v0
	v_ashrrev_i32_e32 v104, 6, v0
	v_mov_b64_e32 v[76:77], v[56:57]
	v_mov_b32_e32 v72, 0
	v_mov_b32_e32 v73, 0
	v_mov_b32_e32 v74, 0
	v_mov_b32_e32 v75, 0
	v_mov_b32_e32 v92, 0
	v_mov_b32_e32 v93, 0
	v_mov_b32_e32 v94, 0
	v_mov_b32_e32 v95, 0
	v_mov_b32_e32 v96, 0
	v_mov_b32_e32 v97, 0
	v_mov_b32_e32 v98, 0
	v_mov_b32_e32 v99, 0
	s_and_saveexec_b64 s[36:37], s[50:51]
	s_cbranch_execz .LBB0_77
	v_add_u32_e32 v0, v104, v103
	s_movk_i32 s0, 0x160
	s_waitcnt lgkmcnt(0)
	v_mul_lo_u32 v2, v0, s0
	v_sub_u32_e32 v2, v102, v2
	v_lshlrev_b32_e32 v4, 3, v2
	v_ashrrev_i32_e32 v2, 1, v0
	v_readlane_b32 s0, v250, 16
	v_add_u32_e32 v6, s30, v2
	v_and_b32_e32 v0, 1, v0
	v_readlane_b32 s1, v250, 17
	v_lshl_or_b32 v12, v6, 1, v0
	s_movk_i32 s2, 0x1600
	v_mov_b64_e32 v[2:3], s[0:1]
	v_mad_u64_u32 v[2:3], s[0:1], v12, s2, v[2:3]
	v_readlane_b32 s0, v250, 18
	v_readlane_b32 s1, v250, 19
	v_ashrrev_i32_e32 v7, 31, v6
	v_ashrrev_i32_e32 v5, 31, v4
	v_mov_b64_e32 v[10:11], s[0:1]
	v_mad_i32_i24 v3, v7, s2, v3
	v_lshlrev_b64 v[8:9], 1, v[4:5]
	v_mad_u64_u32 v[10:11], s[0:1], v12, s2, v[10:11]
	v_lshl_add_u64 v[2:3], v[2:3], 0, v[8:9]
	v_mad_i32_i24 v11, v7, s2, v11
	v_lshl_add_u64 v[8:9], v[10:11], 0, v[8:9]
	global_load_dwordx4 v[72:75], v[2:3], off
	global_load_dwordx4 v[92:95], v[8:9], off
	v_and_b32_e32 v2, 31, v6
	v_cmp_ne_u32_e32 vcc, 0, v2
	v_cmp_eq_u32_e64 s[0:1], 1, v0
	s_mov_b64 s[40:41], 0
	v_mov_b32_e32 v76, 0
	v_mov_b32_e32 v77, 0
	v_mov_b32_e32 v78, 0
	v_mov_b32_e32 v79, 0
	s_and_saveexec_b64 s[2:3], s[0:1]
	s_xor_b64 s[0:1], exec, s[2:3]
	s_cbranch_execz .LBB0_70
	v_readlane_b32 s2, v250, 16
	v_readlane_b32 s3, v250, 17
	s_nop 1
	v_mov_b64_e32 v[2:3], s[2:3]
	s_movk_i32 s2, 0x2c00
	v_mad_i64_i32 v[2:3], s[2:3], v6, s2, v[2:3]
	v_lshl_add_u64 v[2:3], v[4:5], 1, v[2:3]
	global_load_dwordx4 v[76:79], v[2:3], off
	s_and_saveexec_b64 s[2:3], vcc
	s_xor_b64 s[42:43], exec, s[2:3]
	s_cbranch_execz .LBB0_69
	v_readlane_b32 s2, v250, 20
	v_readlane_b32 s3, v250, 21
	v_add_u32_e32 v0, -1, v6
	s_mov_b64 s[40:41], exec
	v_mov_b64_e32 v[2:3], s[2:3]
	s_movk_i32 s2, 0x2c00
	v_mad_i64_i32 v[2:3], s[2:3], v0, s2, v[2:3]
	s_mov_b64 s[2:3], 0x1600
	s_nop 0
	v_lshl_add_u64 v[2:3], v[2:3], 0, s[2:3]

; __device__ __forceinline__ void act_fixup(const Params& p, int l, int pm) {
;     ...
;             if (rr == 0) { if (!seq0) { r1[k] = *(const u32x4*)(gs23 + ((size_t)(blk - 1) * 2 + 1) * DFF + c0); r2[k] = *(const u32x4*)(gs23 + ((size_t)(blk - 1) * 2 + 0) * DFF + c0); } }
;             else { r1[k] = *(const u32x4*)(gs01 + ((size_t)blk * 2 + 0) * DFF + c0); if (!seq0) r2[k] = *(const u32x4*)(gs23 + ((size_t)(blk - 1) * 2 + 1) * DFF + c0); }
.LBB0_70:
	s_andn2_saveexec_b64 s[0:1], s[0:1]
	s_cbranch_execz .LBB0_74
	v_mov_b32_e32 v2, v1
	v_mov_b32_e32 v3, v1
	v_mov_b32_e32 v0, v1
	s_mov_b64 s[42:43], s[40:41]
	s_and_saveexec_b64 s[44:45], vcc
	s_cbranch_execz .LBB0_73
	v_readlane_b32 s2, v250, 20
	v_readlane_b32 s3, v250, 21
	v_add_u32_e32 v0, -1, v6
	s_or_b64 s[42:43], s[40:41], exec
	v_mov_b64_e32 v[2:3], s[2:3]
	s_movk_i32 s2, 0x2c00
	v_mad_i64_i32 v[2:3], s[2:3], v0, s2, v[2:3]
	v_lshl_add_u64 v[6:7], v[4:5], 1, v[2:3]
	v_add_co_u32_e32 v6, vcc, 0x1000, v6
	s_nop 1
	v_addc_co_u32_e32 v7, vcc, 0, v7, vcc
	global_load_dwordx4 v[76:79], v[6:7], off offset:1536

; __device__ __forceinline__ void act_fixup(const Params& p, int l, int pm) {
;     ...
;     for (int k = 0; k < NK; ++k) {
;         const int idx = tid + 512 * k;
;         rg[k] = ru[k] = r1[k] = r2[k] = (u32x4){0u, 0u, 0u, 0u};
;         if (idx < NU) {
;             const int rsel = idx / (DFF / 8), c0 = (idx % (DFF / 8)) * 8, blk = pm * 4 + (rsel >> 1), rr = rsel & 1;
;             const bool seq0 = (blk & 31) == 0;
;             rg[k] = *(const u32x4*)(gs01 + ((size_t)blk * 2 + rr) * DFF + c0);
;             ru[k] = *(const u32x4*)(us01 + ((size_t)blk * 2 + rr) * DFF + c0);
;             if (rr == 0) { if (!seq0) { r1[k] = *(const u32x4*)(gs23 + ((size_t)(blk - 1) * 2 + 1) * DFF + c0); r2[k] = *(const u32x4*)(gs23 + ((size_t)(blk - 1) * 2 + 0) * DFF + c0); } }
.LBB0_77:
	s_or_b64 exec, exec, s[36:37]
	s_movk_i32 s0, 0x900
	v_add_u32_e32 v138, 0x200, v102
	v_cmp_gt_i32_e64 s[48:49], s0, v102
	s_mov_b32 s0, 0x2e8ba2e9
	v_mul_hi_i32 v0, v138, s0
	v_lshrrev_b32_e32 v139, 31, v0
	v_ashrrev_i32_e32 v140, 6, v0
	v_mov_b32_e32 v49, 0
	v_mov_b32_e32 v50, 0
	v_mov_b32_e32 v51, 0
	v_mov_b32_e32 v84, 0
	v_mov_b32_e32 v85, 0
	v_mov_b32_e32 v86, 0
	v_mov_b32_e32 v87, 0
	v_mov_b32_e32 v88, 0
	v_mov_b32_e32 v89, 0
	v_mov_b32_e32 v90, 0
	v_mov_b32_e32 v91, 0
	s_and_saveexec_b64 s[36:37], s[48:49]
	s_cbranch_execz .LBB0_89
	v_add_u32_e32 v0, v140, v139
	s_movk_i32 s0, 0x160
	s_waitcnt lgkmcnt(0)
	v_mul_lo_u32 v2, v0, s0
	v_sub_u32_e32 v2, v138, v2
	v_lshlrev_b32_e32 v4, 3, v2
	v_ashrrev_i32_e32 v2, 1, v0
	v_readlane_b32 s0, v250, 16
	v_add_u32_e32 v6, s30, v2
	v_and_b32_e32 v0, 1, v0
	v_readlane_b32 s1, v250, 17
	v_lshl_or_b32 v12, v6, 1, v0
	s_movk_i32 s2, 0x1600
	v_mov_b64_e32 v[2:3], s[0:1]
	v_mad_u64_u32 v[2:3], s[0:1], v12, s2, v[2:3]
	v_readlane_b32 s0, v250, 18
	v_readlane_b32 s1, v250, 19
	v_ashrrev_i32_e32 v7, 31, v6
	v_ashrrev_i32_e32 v5, 31, v4
	v_mov_b64_e32 v[10:11], s[0:1]
	v_mad_i32_i24 v3, v7, s2, v3
	v_lshlrev_b64 v[8:9], 1, v[4:5]
	v_mad_u64_u32 v[10:11], s[0:1], v12, s2, v[10:11]
	v_lshl_add_u64 v[2:3], v[2:3], 0, v[8:9]
	v_mad_i32_i24 v11, v7, s2, v11
	v_lshl_add_u64 v[8:9], v[10:11], 0, v[8:9]
	global_load_dwordx4 v[48:51], v[2:3], off
	global_load_dwordx4 v[84:87], v[8:9], off
	v_and_b32_e32 v2, 31, v6
	v_cmp_ne_u32_e32 vcc, 0, v2
	v_cmp_eq_u32_e64 s[0:1], 1, v0
	s_mov_b64 s[40:41], 0
	v_mov_b32_e32 v56, 0
	v_mov_b32_e32 v57, 0
	v_mov_b32_e32 v58, 0
	v_mov_b32_e32 v59, 0
	s_and_saveexec_b64 s[2:3], s[0:1]
	s_xor_b64 s[0:1], exec, s[2:3]
	s_cbranch_execz .LBB0_82
	v_readlane_b32 s2, v250, 16
	v_readlane_b32 s3, v250, 17
	s_nop 1
	v_mov_b64_e32 v[2:3], s[2:3]
	s_movk_i32 s2, 0x2c00
	v_mad_i64_i32 v[2:3], s[2:3], v6, s2, v[2:3]
	v_lshl_add_u64 v[2:3], v[4:5], 1, v[2:3]
	global_load_dwordx4 v[56:59], v[2:3], off
	s_and_saveexec_b64 s[42:43], vcc
	s_cbranch_execz .LBB0_81
	v_readlane_b32 s2, v250, 20
	v_readlane_b32 s3, v250, 21
	v_add_u32_e32 v0, -1, v6
	s_mov_b64 s[40:41], exec
	v_mov_b64_e32 v[2:3], s[2:3]
	s_movk_i32 s2, 0x2c00
	v_mad_i64_i32 v[2:3], s[2:3], v0, s2, v[2:3]
	s_mov_b64 s[2:3], 0x1600
	s_nop 0
	v_lshl_add_u64 v[2:3], v[2:3], 0, s[2:3]

; __device__ __forceinline__ void act_fixup(const Params& p, int l, int pm) {
;     ...
;             if (rr == 0) { if (!seq0) { r1[k] = *(const u32x4*)(gs23 + ((size_t)(blk - 1) * 2 + 1) * DFF + c0); r2[k] = *(const u32x4*)(gs23 + ((size_t)(blk - 1) * 2 + 0) * DFF + c0); } }
;             else { r1[k] = *(const u32x4*)(gs01 + ((size_t)blk * 2 + 0) * DFF + c0); if (!seq0) r2[k] = *(const u32x4*)(gs23 + ((size_t)(blk - 1) * 2 + 1) * DFF + c0); }
.LBB0_82:
	s_andn2_saveexec_b64 s[0:1], s[0:1]
	s_cbranch_execz .LBB0_86
	v_mov_b32_e32 v2, v1
	v_mov_b32_e32 v3, v1
	v_mov_b32_e32 v0, v1
	s_mov_b64 s[42:43], s[40:41]
	s_and_saveexec_b64 s[44:45], vcc
	s_cbranch_execz .LBB0_85
	v_readlane_b32 s2, v250, 20
	v_readlane_b32 s3, v250, 21
	v_add_u32_e32 v0, -1, v6
	s_or_b64 s[42:43], s[40:41], exec
	v_mov_b64_e32 v[2:3], s[2:3]
	s_movk_i32 s2, 0x2c00
	v_mad_i64_i32 v[2:3], s[2:3], v0, s2, v[2:3]
	v_lshl_add_u64 v[6:7], v[4:5], 1, v[2:3]
	v_add_co_u32_e32 v6, vcc, 0x1000, v6
	s_nop 1
	v_addc_co_u32_e32 v7, vcc, 0, v7, vcc
	global_load_dwordx4 v[56:59], v[6:7], off offset:1536

; __device__ __forceinline__ void act_fixup(const Params& p, int l, int pm) {
;     ...
;     for (int k = 0; k < NK; ++k) {
;         const int idx = tid + 512 * k;
;         rg[k] = ru[k] = r1[k] = r2[k] = (u32x4){0u, 0u, 0u, 0u};
;         if (idx < NU) {
;             const int rsel = idx / (DFF / 8), c0 = (idx % (DFF / 8)) * 8, blk = pm * 4 + (rsel >> 1), rr = rsel & 1;
;             const bool seq0 = (blk & 31) == 0;
;             rg[k] = *(const u32x4*)(gs01 + ((size_t)blk * 2 + rr) * DFF + c0);
;             ru[k] = *(const u32x4*)(us01 + ((size_t)blk * 2 + rr) * DFF + c0);
;             if (rr == 0) { if (!seq0) { r1[k] = *(const u32x4*)(gs23 + ((size_t)(blk - 1) * 2 + 1) * DFF + c0); r2[k] = *(const u32x4*)(gs23 + ((size_t)(blk - 1) * 2 + 0) * DFF + c0); } }
.LBB0_89:
	s_or_b64 exec, exec, s[36:37]
	s_movk_i32 s0, 0x700
	v_add_u32_e32 v135, 0x400, v102
	v_cmp_gt_i32_e64 s[46:47], s0, v102
	s_waitcnt lgkmcnt(0)
	v_mov_b32_e32 v2, v1
	v_mov_b32_e32 v3, v1
	s_mov_b32 s0, 0x2e8ba2e9
	v_mov_b32_e32 v0, v1
	v_mul_hi_i32 v4, v135, s0
	v_mov_b64_e32 v[46:47], v[2:3]
	v_mov_b32_e32 v20, 0
	v_lshrrev_b32_e32 v136, 31, v4
	v_ashrrev_i32_e32 v137, 6, v4
	v_mov_b64_e32 v[44:45], v[0:1]
	v_mov_b32_e32 v40, 0
	v_mov_b32_e32 v41, 0
	v_mov_b32_e32 v42, 0
	v_mov_b32_e32 v43, 0
	v_mov_b32_e32 v68, 0
	v_mov_b32_e32 v69, 0
	v_mov_b32_e32 v70, 0
	v_mov_b32_e32 v71, 0
	v_mov_b32_e32 v80, 0
	v_mov_b32_e32 v81, 0
	v_mov_b32_e32 v82, 0
	v_mov_b32_e32 v83, 0
	s_and_saveexec_b64 s[36:37], s[46:47]
	s_cbranch_execz .LBB0_101
	v_add_u32_e32 v5, v137, v136
	s_movk_i32 s0, 0x160
	v_mul_lo_u32 v4, v5, s0
	v_ashrrev_i32_e32 v6, 1, v5
	v_readlane_b32 s0, v250, 16
	v_add_u32_e32 v8, s30, v6
	v_and_b32_e32 v9, 1, v5
	v_readlane_b32 s1, v250, 17
	v_lshl_or_b32 v15, v8, 1, v9
	s_movk_i32 s2, 0x1600
	v_mov_b64_e32 v[6:7], s[0:1]
	v_mad_u64_u32 v[6:7], s[0:1], v15, s2, v[6:7]
	v_sub_u32_e32 v4, v135, v4
	v_readlane_b32 s0, v250, 18
	v_lshlrev_b32_e32 v4, 3, v4
	v_readlane_b32 s1, v250, 19
	v_ashrrev_i32_e32 v14, 31, v8
	v_ashrrev_i32_e32 v5, 31, v4
	v_mov_b64_e32 v[12:13], s[0:1]
	v_mad_i32_i24 v7, v14, s2, v7
	v_lshlrev_b64 v[10:11], 1, v[4:5]
	v_mad_u64_u32 v[12:13], s[0:1], v15, s2, v[12:13]
	v_lshl_add_u64 v[6:7], v[6:7], 0, v[10:11]
	v_mad_i32_i24 v13, v14, s2, v13
	v_lshl_add_u64 v[10:11], v[12:13], 0, v[10:11]
	global_load_dwordx4 v[40:43], v[6:7], off
	global_load_dwordx4 v[68:71], v[10:11], off
	v_and_b32_e32 v6, 31, v8
	v_cmp_ne_u32_e32 vcc, 0, v6
	v_cmp_eq_u32_e64 s[0:1], 1, v9
	s_mov_b64 s[40:41], 0
	v_mov_b32_e32 v44, 0
	v_mov_b32_e32 v45, 0
	v_mov_b32_e32 v46, 0
	v_mov_b32_e32 v47, 0
	s_and_saveexec_b64 s[2:3], s[0:1]
	s_xor_b64 s[0:1], exec, s[2:3]
	s_cbranch_execz .LBB0_94
	v_readlane_b32 s2, v250, 16
	v_readlane_b32 s3, v250, 17
	s_nop 1
	v_mov_b64_e32 v[6:7], s[2:3]
	s_movk_i32 s2, 0x2c00
	v_mad_i64_i32 v[6:7], s[2:3], v8, s2, v[6:7]
	v_lshl_add_u64 v[6:7], v[4:5], 1, v[6:7]
	global_load_dwordx4 v[44:47], v[6:7], off
	s_and_saveexec_b64 s[42:43], vcc
	s_cbranch_execz .LBB0_93
	v_readlane_b32 s2, v250, 20
	v_readlane_b32 s3, v250, 21
	v_add_u32_e32 v8, -1, v8
	s_mov_b64 s[40:41], exec
	v_mov_b64_e32 v[6:7], s[2:3]
	s_movk_i32 s2, 0x2c00
	v_mad_i64_i32 v[6:7], s[2:3], v8, s2, v[6:7]
	s_mov_b64 s[2:3], 0x1600
	s_nop 0
	v_lshl_add_u64 v[6:7], v[6:7], 0, s[2:3]

; __device__ __forceinline__ void act_fixup(const Params& p, int l, int pm) {
;     ...
;             if (rr == 0) { if (!seq0) { r1[k] = *(const u32x4*)(gs23 + ((size_t)(blk - 1) * 2 + 1) * DFF + c0); r2[k] = *(const u32x4*)(gs23 + ((size_t)(blk - 1) * 2 + 0) * DFF + c0); } }
;             else { r1[k] = *(const u32x4*)(gs01 + ((size_t)blk * 2 + 0) * DFF + c0); if (!seq0) r2[k] = *(const u32x4*)(gs23 + ((size_t)(blk - 1) * 2 + 1) * DFF + c0); }
.LBB0_94:
	s_andn2_saveexec_b64 s[0:1], s[0:1]
	s_cbranch_execz .LBB0_98
	s_mov_b64 s[42:43], s[40:41]
	s_and_saveexec_b64 s[44:45], vcc
	s_cbranch_execz .LBB0_97
	v_readlane_b32 s2, v250, 20
	v_readlane_b32 s3, v250, 21
	v_add_u32_e32 v8, -1, v8
	s_or_b64 s[42:43], s[40:41], exec
	v_mov_b64_e32 v[6:7], s[2:3]
	s_movk_i32 s2, 0x2c00
	v_mad_i64_i32 v[6:7], s[2:3], v8, s2, v[6:7]
	v_lshl_add_u64 v[8:9], v[4:5], 1, v[6:7]
	v_add_co_u32_e32 v8, vcc, 0x1000, v8
	s_nop 1
	v_addc_co_u32_e32 v9, vcc, 0, v9, vcc
	global_load_dwordx4 v[44:47], v[8:9], off offset:1536

; __device__ __forceinline__ void act_fixup(const Params& p, int l, int pm) {
;     ...
;     for (int k = 0; k < NK; ++k) {
;         const int idx = tid + 512 * k;
;         rg[k] = ru[k] = r1[k] = r2[k] = (u32x4){0u, 0u, 0u, 0u};
;         if (idx < NU) {
;             const int rsel = idx / (DFF / 8), c0 = (idx % (DFF / 8)) * 8, blk = pm * 4 + (rsel >> 1), rr = rsel & 1;
;             const bool seq0 = (blk & 31) == 0;
;             rg[k] = *(const u32x4*)(gs01 + ((size_t)blk * 2 + rr) * DFF + c0);
;             ru[k] = *(const u32x4*)(us01 + ((size_t)blk * 2 + rr) * DFF + c0);
;             if (rr == 0) { if (!seq0) { r1[k] = *(const u32x4*)(gs23 + ((size_t)(blk - 1) * 2 + 1) * DFF + c0); r2[k] = *(const u32x4*)(gs23 + ((size_t)(blk - 1) * 2 + 0) * DFF + c0); } }
.LBB0_101:
	s_or_b64 exec, exec, s[36:37]
	s_movk_i32 s0, 0x500
	v_add_u32_e32 v132, 0x600, v102
	v_cmp_gt_i32_e64 s[44:45], s0, v102
	s_mov_b32 s0, 0x2e8ba2e9
	v_mul_hi_i32 v4, v132, s0
	v_mov_b64_e32 v[30:31], v[2:3]
	v_lshrrev_b32_e32 v133, 31, v4
	v_ashrrev_i32_e32 v134, 6, v4
	v_mov_b64_e32 v[28:29], v[0:1]
	v_mov_b32_e32 v21, 0
	v_mov_b32_e32 v22, 0
	s_waitcnt lgkmcnt(0)
	v_mov_b32_e32 v23, 0
	v_mov_b32_e32 v60, 0
	v_mov_b32_e32 v61, 0
	v_mov_b32_e32 v62, 0
	v_mov_b32_e32 v63, 0
	v_mov_b32_e32 v64, 0
	v_mov_b32_e32 v65, 0
	v_mov_b32_e32 v66, 0
	v_mov_b32_e32 v67, 0
	s_and_saveexec_b64 s[36:37], s[44:45]
	s_cbranch_execz .LBB0_113
	v_add_u32_e32 v0, v134, v133
	s_movk_i32 s0, 0x160
	v_mul_lo_u32 v2, v0, s0
	v_sub_u32_e32 v2, v132, v2
	v_lshlrev_b32_e32 v4, 3, v2
	v_ashrrev_i32_e32 v2, 1, v0
	v_readlane_b32 s0, v250, 16
	v_add_u32_e32 v6, s30, v2
	v_and_b32_e32 v0, 1, v0
	v_readlane_b32 s1, v250, 17
	v_lshl_or_b32 v12, v6, 1, v0
	s_movk_i32 s2, 0x1600
	v_mov_b64_e32 v[2:3], s[0:1]
	v_mad_u64_u32 v[2:3], s[0:1], v12, s2, v[2:3]
	v_readlane_b32 s0, v250, 18
	v_readlane_b32 s1, v250, 19
	v_ashrrev_i32_e32 v7, 31, v6
	v_ashrrev_i32_e32 v5, 31, v4
	v_mov_b64_e32 v[10:11], s[0:1]
	v_mad_i32_i24 v3, v7, s2, v3
	v_lshlrev_b64 v[8:9], 1, v[4:5]
	v_mad_u64_u32 v[10:11], s[0:1], v12, s2, v[10:11]
	v_lshl_add_u64 v[2:3], v[2:3], 0, v[8:9]
	v_mad_i32_i24 v11, v7, s2, v11
	v_lshl_add_u64 v[8:9], v[10:11], 0, v[8:9]
	global_load_dwordx4 v[20:23], v[2:3], off
	global_load_dwordx4 v[60:63], v[8:9], off
	v_and_b32_e32 v2, 31, v6
	v_cmp_ne_u32_e32 vcc, 0, v2
	v_cmp_eq_u32_e64 s[0:1], 1, v0
	s_mov_b64 s[40:41], 0
	v_mov_b32_e32 v28, 0
	v_mov_b32_e32 v29, 0
	v_mov_b32_e32 v30, 0
	v_mov_b32_e32 v31, 0
	s_and_saveexec_b64 s[2:3], s[0:1]
	s_xor_b64 s[0:1], exec, s[2:3]
	s_cbranch_execz .LBB0_106
	v_readlane_b32 s2, v250, 16
	v_readlane_b32 s3, v250, 17
	s_nop 1
	v_mov_b64_e32 v[2:3], s[2:3]
	s_movk_i32 s2, 0x2c00
	v_mad_i64_i32 v[2:3], s[2:3], v6, s2, v[2:3]
	v_lshl_add_u64 v[2:3], v[4:5], 1, v[2:3]
	global_load_dwordx4 v[28:31], v[2:3], off
	s_and_saveexec_b64 s[42:43], vcc
	s_cbranch_execz .LBB0_105
	v_readlane_b32 s2, v250, 20
	v_readlane_b32 s3, v250, 21
	v_add_u32_e32 v0, -1, v6
	s_mov_b64 s[40:41], exec
	v_mov_b64_e32 v[2:3], s[2:3]
	s_movk_i32 s2, 0x2c00
	v_mad_i64_i32 v[2:3], s[2:3], v0, s2, v[2:3]
	s_mov_b64 s[2:3], 0x1600
	s_nop 0
	v_lshl_add_u64 v[2:3], v[2:3], 0, s[2:3]

; __device__ __forceinline__ void act_fixup(const Params& p, int l, int pm) {
;     ...
;             if (rr == 0) { if (!seq0) { r1[k] = *(const u32x4*)(gs23 + ((size_t)(blk - 1) * 2 + 1) * DFF + c0); r2[k] = *(const u32x4*)(gs23 + ((size_t)(blk - 1) * 2 + 0) * DFF + c0); } }
;             else { r1[k] = *(const u32x4*)(gs01 + ((size_t)blk * 2 + 0) * DFF + c0); if (!seq0) r2[k] = *(const u32x4*)(gs23 + ((size_t)(blk - 1) * 2 + 1) * DFF + c0); }
.LBB0_106:
	s_andn2_saveexec_b64 s[0:1], s[0:1]
	s_cbranch_execz .LBB0_110
	v_mov_b32_e32 v2, v1
	v_mov_b32_e32 v3, v1
	v_mov_b32_e32 v0, v1
	s_mov_b64 s[42:43], s[40:41]
	s_and_saveexec_b64 s[52:53], vcc
	s_cbranch_execz .LBB0_109
	v_readlane_b32 s2, v250, 20
	v_readlane_b32 s3, v250, 21
	v_add_u32_e32 v0, -1, v6
	s_or_b64 s[42:43], s[40:41], exec
	v_mov_b64_e32 v[2:3], s[2:3]
	s_movk_i32 s2, 0x2c00
	v_mad_i64_i32 v[2:3], s[2:3], v0, s2, v[2:3]
	v_lshl_add_u64 v[6:7], v[4:5], 1, v[2:3]
	v_add_co_u32_e32 v6, vcc, 0x1000, v6
	s_nop 1
	v_addc_co_u32_e32 v7, vcc, 0, v7, vcc
	global_load_dwordx4 v[28:31], v[6:7], off offset:1536

; __device__ __forceinline__ void act_fixup(const Params& p, int l, int pm) {
;     ...
;     for (int k = 0; k < NK; ++k) {
;         const int idx = tid + 512 * k;
;         rg[k] = ru[k] = r1[k] = r2[k] = (u32x4){0u, 0u, 0u, 0u};
;         if (idx < NU) {
;             const int rsel = idx / (DFF / 8), c0 = (idx % (DFF / 8)) * 8, blk = pm * 4 + (rsel >> 1), rr = rsel & 1;
;             const bool seq0 = (blk & 31) == 0;
;             rg[k] = *(const u32x4*)(gs01 + ((size_t)blk * 2 + rr) * DFF + c0);
;             ru[k] = *(const u32x4*)(us01 + ((size_t)blk * 2 + rr) * DFF + c0);
;             if (rr == 0) { if (!seq0) { r1[k] = *(const u32x4*)(gs23 + ((size_t)(blk - 1) * 2 + 1) * DFF + c0); r2[k] = *(const u32x4*)(gs23 + ((size_t)(blk - 1) * 2 + 0) * DFF + c0); } }
.LBB0_113:
	s_or_b64 exec, exec, s[36:37]
	s_movk_i32 s0, 0x300
	v_add_u32_e32 v129, 0x800, v102
	v_cmp_gt_i32_e64 s[42:43], s0, v102
	v_mov_b32_e32 v2, v1
	v_mov_b32_e32 v3, v1
	s_mov_b32 s0, 0x2e8ba2e9
	v_mov_b32_e32 v0, v1
	v_mul_hi_i32 v5, v129, s0
	v_mov_b64_e32 v[18:19], v[2:3]
	v_mov_b32_e32 v4, 0
	v_lshrrev_b32_e32 v130, 31, v5
	v_ashrrev_i32_e32 v131, 6, v5
	v_mov_b64_e32 v[16:17], v[0:1]
	v_mov_b32_e32 v12, 0
	v_mov_b32_e32 v13, 0
	v_mov_b32_e32 v14, 0
	v_mov_b32_e32 v15, 0
	v_mov_b32_e32 v36, 0
	v_mov_b32_e32 v37, 0
	v_mov_b32_e32 v38, 0
	v_mov_b32_e32 v39, 0
	v_mov_b32_e32 v52, 0
	v_mov_b32_e32 v53, 0
	v_mov_b32_e32 v54, 0
	v_mov_b32_e32 v55, 0
	s_and_saveexec_b64 s[36:37], s[42:43]
	s_cbranch_execz .LBB0_125
	v_add_u32_e32 v5, v131, v130
	s_movk_i32 s0, 0x160
	v_mul_lo_u32 v6, v5, s0
	v_ashrrev_i32_e32 v7, 1, v5
	v_readlane_b32 s0, v250, 16
	v_add_u32_e32 v10, s30, v7
	v_and_b32_e32 v5, 1, v5
	v_readlane_b32 s1, v250, 17
	v_lshl_or_b32 v16, v10, 1, v5
	s_movk_i32 s2, 0x1600
	v_mov_b64_e32 v[8:9], s[0:1]
	v_mad_u64_u32 v[8:9], s[0:1], v16, s2, v[8:9]
	v_sub_u32_e32 v6, v129, v6
	v_readlane_b32 s0, v250, 18
	v_lshlrev_b32_e32 v6, 3, v6
	v_readlane_b32 s1, v250, 19
	v_ashrrev_i32_e32 v11, 31, v10
	v_ashrrev_i32_e32 v7, 31, v6
	v_mov_b64_e32 v[14:15], s[0:1]
	v_mad_i32_i24 v9, v11, s2, v9
	v_lshlrev_b64 v[12:13], 1, v[6:7]
	v_mad_u64_u32 v[14:15], s[0:1], v16, s2, v[14:15]
	v_lshl_add_u64 v[8:9], v[8:9], 0, v[12:13]
	v_mad_i32_i24 v15, v11, s2, v15
	v_lshl_add_u64 v[16:17], v[14:15], 0, v[12:13]
	global_load_dwordx4 v[12:15], v[8:9], off
	global_load_dwordx4 v[36:39], v[16:17], off
	v_and_b32_e32 v8, 31, v10
	v_cmp_ne_u32_e32 vcc, 0, v8
	v_cmp_eq_u32_e64 s[0:1], 1, v5
	s_mov_b64 s[40:41], 0
	v_mov_b32_e32 v16, 0
	v_mov_b32_e32 v17, 0
	v_mov_b32_e32 v18, 0
	v_mov_b32_e32 v19, 0
	s_and_saveexec_b64 s[2:3], s[0:1]
	s_xor_b64 s[0:1], exec, s[2:3]
	s_cbranch_execz .LBB0_118
	v_readlane_b32 s2, v250, 16
	v_readlane_b32 s3, v250, 17
	s_nop 1
	v_mov_b64_e32 v[8:9], s[2:3]
	s_movk_i32 s2, 0x2c00
	v_mad_i64_i32 v[8:9], s[2:3], v10, s2, v[8:9]
	v_lshl_add_u64 v[8:9], v[6:7], 1, v[8:9]
	global_load_dwordx4 v[16:19], v[8:9], off
	s_and_saveexec_b64 s[52:53], vcc
	s_cbranch_execz .LBB0_117
	v_readlane_b32 s2, v250, 20
	v_readlane_b32 s3, v250, 21
	v_add_u32_e32 v5, -1, v10
	s_mov_b64 s[40:41], exec
	v_mov_b64_e32 v[8:9], s[2:3]
	s_movk_i32 s2, 0x2c00
	v_mad_i64_i32 v[8:9], s[2:3], v5, s2, v[8:9]
	s_mov_b64 s[2:3], 0x1600
	s_nop 0
	v_lshl_add_u64 v[8:9], v[8:9], 0, s[2:3]

; __device__ __forceinline__ void act_fixup(const Params& p, int l, int pm) {
;     ...
;             if (rr == 0) { if (!seq0) { r1[k] = *(const u32x4*)(gs23 + ((size_t)(blk - 1) * 2 + 1) * DFF + c0); r2[k] = *(const u32x4*)(gs23 + ((size_t)(blk - 1) * 2 + 0) * DFF + c0); } }
;             else { r1[k] = *(const u32x4*)(gs01 + ((size_t)blk * 2 + 0) * DFF + c0); if (!seq0) r2[k] = *(const u32x4*)(gs23 + ((size_t)(blk - 1) * 2 + 1) * DFF + c0); }
.LBB0_118:
	s_andn2_saveexec_b64 s[0:1], s[0:1]
	s_cbranch_execz .LBB0_122
	s_mov_b64 s[52:53], s[40:41]
	s_and_saveexec_b64 s[54:55], vcc
	s_cbranch_execz .LBB0_121
	v_readlane_b32 s2, v250, 20
	v_readlane_b32 s3, v250, 21
	v_add_u32_e32 v5, -1, v10
	s_or_b64 s[52:53], s[40:41], exec
	v_mov_b64_e32 v[8:9], s[2:3]
	s_movk_i32 s2, 0x2c00
	v_mad_i64_i32 v[8:9], s[2:3], v5, s2, v[8:9]
	v_lshl_add_u64 v[10:11], v[6:7], 1, v[8:9]
	v_add_co_u32_e32 v10, vcc, 0x1000, v10
	s_nop 1
	v_addc_co_u32_e32 v11, vcc, 0, v11, vcc
	global_load_dwordx4 v[16:19], v[10:11], off offset:1536

; __device__ __forceinline__ void act_fixup(const Params& p, int l, int pm) {
;     ...
;     for (int k = 0; k < NK; ++k) {
;         const int idx = tid + 512 * k;
;         rg[k] = ru[k] = r1[k] = r2[k] = (u32x4){0u, 0u, 0u, 0u};
;         if (idx < NU) {
;             const int rsel = idx / (DFF / 8), c0 = (idx % (DFF / 8)) * 8, blk = pm * 4 + (rsel >> 1), rr = rsel & 1;
;             const bool seq0 = (blk & 31) == 0;
;             rg[k] = *(const u32x4*)(gs01 + ((size_t)blk * 2 + rr) * DFF + c0);
;             ru[k] = *(const u32x4*)(us01 + ((size_t)blk * 2 + rr) * DFF + c0);
;             if (rr == 0) { if (!seq0) { r1[k] = *(const u32x4*)(gs23 + ((size_t)(blk - 1) * 2 + 1) * DFF + c0); r2[k] = *(const u32x4*)(gs23 + ((size_t)(blk - 1) * 2 + 0) * DFF + c0); } }
.LBB0_132:
	v_add_u32_e32 v0, v128, v127
	s_movk_i32 s0, 0x160
	v_mul_lo_u32 v2, v0, s0
	v_sub_u32_e32 v2, v126, v2
	v_lshlrev_b32_e32 v100, 3, v2
	v_ashrrev_i32_e32 v2, 1, v0
	v_readlane_b32 s0, v250, 16
	v_add_u32_e32 v32, s30, v2
	v_and_b32_e32 v0, 1, v0
	v_readlane_b32 s1, v250, 17
	v_lshl_or_b32 v9, v32, 1, v0
	s_movk_i32 s2, 0x1600
	v_mov_b64_e32 v[2:3], s[0:1]
	v_mad_u64_u32 v[2:3], s[0:1], v9, s2, v[2:3]
	v_readlane_b32 s0, v250, 18
	v_readlane_b32 s1, v250, 19
	v_ashrrev_i32_e32 v8, 31, v32
	v_ashrrev_i32_e32 v101, 31, v100
	v_mov_b64_e32 v[6:7], s[0:1]
	v_mad_i32_i24 v3, v8, s2, v3
	v_lshlrev_b64 v[4:5], 1, v[100:101]
	v_mad_u64_u32 v[6:7], s[0:1], v9, s2, v[6:7]
	v_lshl_add_u64 v[2:3], v[2:3], 0, v[4:5]
	v_mad_i32_i24 v7, v8, s2, v7
	v_lshl_add_u64 v[8:9], v[6:7], 0, v[4:5]
	global_load_dwordx4 v[4:7], v[2:3], off
	global_load_dwordx4 v[24:27], v[8:9], off
	v_and_b32_e32 v2, 31, v32
	v_cmp_ne_u32_e32 vcc, 0, v2
	v_cmp_eq_u32_e64 s[0:1], 1, v0
	s_mov_b64 s[52:53], 0
	v_mov_b32_e32 v8, 0
	v_mov_b32_e32 v9, 0
	v_mov_b32_e32 v10, 0
	v_mov_b32_e32 v11, 0
	s_and_saveexec_b64 s[2:3], s[0:1]
	s_xor_b64 s[0:1], exec, s[2:3]
	s_cbranch_execz .LBB0_136
	v_readlane_b32 s2, v250, 16
	v_readlane_b32 s3, v250, 17
	s_nop 1
	v_mov_b64_e32 v[2:3], s[2:3]
	s_movk_i32 s2, 0x2c00
	v_mad_i64_i32 v[2:3], s[2:3], v32, s2, v[2:3]
	v_lshl_add_u64 v[2:3], v[100:101], 1, v[2:3]
	global_load_dwordx4 v[8:11], v[2:3], off
	s_and_saveexec_b64 s[54:55], vcc
	s_cbranch_execz .LBB0_135
	v_readlane_b32 s2, v250, 20
	v_readlane_b32 s3, v250, 21
	v_add_u32_e32 v0, -1, v32
	s_mov_b64 s[52:53], exec
	v_mov_b64_e32 v[2:3], s[2:3]
	s_movk_i32 s2, 0x2c00
	v_mad_i64_i32 v[2:3], s[2:3], v0, s2, v[2:3]
	s_mov_b64 s[2:3], 0x1600
	s_nop 0
	v_lshl_add_u64 v[2:3], v[2:3], 0, s[2:3]

; __device__ __forceinline__ void act_fixup(const Params& p, int l, int pm) {
;     ...
;             if (rr == 0) { if (!seq0) { r1[k] = *(const u32x4*)(gs23 + ((size_t)(blk - 1) * 2 + 1) * DFF + c0); r2[k] = *(const u32x4*)(gs23 + ((size_t)(blk - 1) * 2 + 0) * DFF + c0); } }
;             else { r1[k] = *(const u32x4*)(gs01 + ((size_t)blk * 2 + 0) * DFF + c0); if (!seq0) r2[k] = *(const u32x4*)(gs23 + ((size_t)(blk - 1) * 2 + 1) * DFF + c0); }
.LBB0_136:
	s_andn2_saveexec_b64 s[0:1], s[0:1]
	s_cbranch_execz .LBB0_140
	v_mov_b32_e32 v2, v1
	v_mov_b32_e32 v3, v1
	v_mov_b32_e32 v0, v1
	s_mov_b64 s[54:55], s[52:53]
	s_and_saveexec_b64 s[62:63], vcc
	s_cbranch_execz .LBB0_139
	v_readlane_b32 s2, v250, 20
	v_readlane_b32 s3, v250, 21
	v_add_u32_e32 v0, -1, v32
	s_or_b64 s[54:55], s[52:53], exec
	v_mov_b64_e32 v[2:3], s[2:3]
	s_movk_i32 s2, 0x2c00
	v_mad_i64_i32 v[2:3], s[2:3], v0, s2, v[2:3]
	v_lshl_add_u64 v[8:9], v[100:101], 1, v[2:3]
	v_add_co_u32_e32 v8, vcc, 0x1000, v8
	s_nop 1
	v_addc_co_u32_e32 v9, vcc, 0, v9, vcc
	global_load_dwordx4 v[8:11], v[8:9], off offset:1536

; #define PG8_STAGE(bufoff, gbase, voff) do { _Pragma("unroll") for (int _i = 0; _i < 2; ++_i) \
;         __builtin_amdgcn_global_load_lds((const unsigned*)((const char*)(gbase) + (voff)[_i]), (LAS unsigned*)(lds + (bufoff) + ldsw + _i * 8192), 16, 0, 0); } while (0)
; #define PG8_WAIT_V(n) asm volatile("s_waitcnt vmcnt(" #n ")" ::: "memory")
; #define PG8_BAR __builtin_amdgcn_s_barrier()
; template <class Epi>
; __device__ __forceinline__ void gemm_phase(LAS unsigned char* lds, const Gemm g, const StaticOrder& S, const Epi& E) {
;     ...
;     for (int i = 0; i < 2; ++i) { int R, C; stage_rc(tid * 16 + i * 8192, R, C); const int Rb = Epi::PERM ? ((R & ~31) + perm32(R & 31)) : R;
;         voffA[i] = (unsigned)(R * K + C) * 2u; voffB[i] = (unsigned)(Rb * K + C) * 2u; }
;     const size_t kstep = (size_t)(BK * 2);
;     const size_t hstep = (size_t)HALF * K * 2;
;     const size_t tstep = 2 * hstep;
;     const unsigned ldsw = (unsigned)wid * 1024u;
;     const int aoff = lds_byte(wr * 64 + fr, fq * 8), boff = lds_byte(wc * 32 + fr, fq * 8);
;     ...
;     Unit cur, nxt; int ui = 0;
;     if (!S.next(0, cur)) return;
;     f32x4 acc[2][2][4][2];
; #pragma unroll
;     for (int a = 0; a < 2; ++a)
; #pragma unroll
;         for (int b = 0; b < 2; ++b)
; #pragma unroll
;             for (int m = 0; m < 4; ++m)
; #pragma unroll
;                 for (int n = 0; n < 2; ++n) acc[a][b][m][n] = (f32x4){0.f, 0.f, 0.f, 0.f};
;     bf16x8 At[4][2], B0[2][2], B1[2][2];
;     const char* cA = (const char*)g.A + (size_t)cur.pm * tstep; const char* cB = (const char*)g.Bt + (size_t)cur.pn * tstep;
;     PG8_STAGE(PG8_SB(0, 0), cB, voffB); PG8_STAGE(PG8_SA(0, 0), cA, voffA); PG8_STAGE(PG8_SB(0, 1), cB + hstep, voffB); PG8_STAGE(PG8_SA(0, 1), cA + hstep, voffA);
;     if (wr == 1) PG8_BAR;
;     PG8_WAIT_V(4); PG8_BAR;
;     PG8_STAGE(PG8_SB(1, 0), cB + kstep, voffB); PG8_STAGE(PG8_SA(1, 0), cA + kstep, voffA); PG8_STAGE(PG8_SB(1, 1), cB + hstep + kstep, voffB);
;     PG8_WAIT_V(6); PG8_BAR;
; __device__ __forceinline__ void run_phase(const Params& p, LAS unsigned char* lds, int ph) {
;     ...
;         { pg8::Unit uu; for (int i = 0; S.next(i, uu); ++i) act_fixup(p, l, uu.pm); __threadfence(); __syncthreads(); }
;         pg8::gemm_phase(lds, pg8::Gemm{act, W, TP, DM, DFF}, S, pg8::EpiResid{DM, xb, r});
.LBB0_149:
	v_readlane_b32 s2, v254, 48
	s_mul_hi_i32 s0, s2, 0x580000
	s_mul_i32 s1, s2, 0x580000
	v_readlane_b32 s2, v254, 46
	s_add_i32 s2, s2, 2
	v_readlane_b32 s24, v250, 7
	v_readlane_b32 s3, v254, 49
	s_add_u32 s78, s24, s1
	v_readlane_b32 s1, v250, 8
	s_mul_hi_i32 s3, s2, 0x20400
	s_mul_i32 s2, s2, 0x20400
	s_addc_u32 s79, s1, s0
	v_readlane_b32 s0, v254, 40
	v_readlane_b32 s1, v254, 41
	s_add_u32 s72, s0, s2
	s_addc_u32 s73, s1, s3
	v_readlane_b32 s0, v250, 22
	s_waitcnt vmcnt(0)
	v_mov_b32_e32 v10, v163
	v_readlane_b32 s1, v250, 23
	s_waitcnt lgkmcnt(0)
	buffer_inv sc1
	s_barrier
	s_andn2_b64 vcc, exec, s[0:1]
	v_readfirstlane_b32 s30, v10
	s_cbranch_vccnz .LBB0_192
	v_lshlrev_b32_e32 v0, 4, v10
	v_add_u32_e32 v2, 0x2000, v0
	v_ashrrev_i32_e32 v3, 31, v2
	v_lshrrev_b32_e32 v3, 22, v3
	v_add_u32_e32 v3, v2, v3
	v_ashrrev_i32_e32 v6, 10, v3
	v_mul_i32_i24_e32 v3, 0x400, v6
	v_sub_u32_e32 v2, v2, v3
	v_lshrrev_b32_e32 v3, 4, v2
	v_bitop3_b32 v2, v3, v2, 32 bitop3:0x6c
	v_ashrrev_i32_e32 v3, 31, v2
	v_lshrrev_b32_e32 v3, 26, v3
	v_add_u32_e32 v3, v2, v3
	v_ashrrev_i32_e32 v7, 6, v3
	v_and_b32_e32 v3, 0xc0, v3
	v_sub_u32_e32 v2, v2, v3
	v_ashrrev_i16_sdwa v2, v228, sext(v2) dst_sel:DWORD dst_unused:UNUSED_PAD src0_sel:DWORD src1_sel:BYTE_0
	v_bfe_i32 v9, v2, 0, 16
	v_bfe_i32 v2, v10, 27, 1
	v_lshrrev_b32_e32 v2, 22, v2
	v_add_u32_e32 v2, v0, v2
	v_and_b32_e32 v2, 0xfffffc00, v2
	v_sub_u32_e32 v0, v0, v2
	v_lshrrev_b32_e32 v2, 4, v0
	v_bitop3_b32 v2, v2, v0, 32 bitop3:0x6c
	v_ashrrev_i32_e32 v0, 31, v0
	v_lshrrev_b32_e32 v0, 26, v0
	v_add_u32_e32 v0, v2, v0
	v_ashrrev_i32_e32 v11, 6, v0
	v_ashrrev_i32_e32 v0, 31, v10
	v_lshrrev_b32_e32 v0, 26, v0
	v_add_u32_e32 v0, v10, v0
	v_ashrrev_i32_e32 v12, 6, v0
	v_lshlrev_b32_e32 v4, 3, v6
	v_lshlrev_b32_e32 v0, 3, v12
	v_and_b32_e32 v4, 0xfffff0, v4
	v_and_b32_e32 v0, 0xfffff0, v0
	v_lshlrev_b32_e32 v3, 5, v12
	s_ashr_i32 s24, s30, 6
	v_add_u32_e32 v4, v7, v4
	s_movk_i32 s0, 0xb00
	v_add_u32_e32 v0, v11, v0
	v_and_b32_e32 v13, 32, v3
	v_mul_i32_i24_e32 v3, 64, v11
	v_readlane_b32 s1, v252, 45
	s_ashr_i32 s26, s30, 8
	s_lshl_b32 s52, s24, 10
	v_mul_lo_u32 v4, v4, s0
	v_mul_lo_u32 v0, v0, s0
	v_sub_u32_e32 v2, v2, v3
	s_mul_i32 s0, s1, 0x160000
	v_lshlrev_b32_e32 v5, 5, v6
	v_ashrrev_i16_sdwa v2, v228, sext(v2) dst_sel:DWORD dst_unused:UNUSED_PAD src0_sel:DWORD src1_sel:BYTE_0
	s_add_u32 s60, s78, s0
	s_mul_hi_i32 s0, s1, 0x160000
	v_and_b32_e32 v8, 32, v5
	v_or_b32_e32 v0, v0, v13
	v_bfe_i32 v14, v2, 0, 16
	s_addc_u32 s61, s79, s0
	s_add_i32 s53, s52, 0
	v_or_b32_e32 v4, v4, v8
	v_add_lshl_u32 v0, v0, v14, 1
	s_add_i32 m0, s53, 0x10000
	v_add_lshl_u32 v130, v4, v9, 1
	global_load_lds_dwordx4 v0, s[60:61]
	s_add_i32 m0, s53, 0x12000
	v_readlane_b32 s0, v252, 59
	global_load_lds_dwordx4 v130, s[60:61]
	s_mov_b32 m0, s53
	v_readlane_b32 s1, v252, 60
	s_add_i32 s54, s53, 0x2000
	v_mov_b32_e32 v131, v1
	v_lshl_add_u64 v[2:3], s[60:61], 0, v[0:1]
	v_lshl_add_u64 v[4:5], s[60:61], 0, v[130:131]
	s_nop 0
	global_load_lds_dwordx4 v0, s[0:1]
	s_mov_b32 m0, s54
	s_nop 0
	global_load_lds_dwordx4 v130, s[0:1]
	s_add_u32 s0, s60, 0xb0000
	s_addc_u32 s1, s61, 0
	s_add_i32 m0, s53, 0x14000
	s_add_i32 s55, s53, 0x4000
	global_load_lds_dwordx4 v0, s[0:1]
	s_add_i32 m0, s53, 0x16000
	s_add_i32 s63, s53, 0x6000
	global_load_lds_dwordx4 v130, s[0:1]
	v_readlane_b32 s0, v252, 61
	s_mov_b32 m0, s55
	v_readlane_b32 s1, v252, 62
	s_cmp_lg_u32 s26, 1
	s_nop 3
	global_load_lds_dwordx4 v0, s[0:1]
	s_mov_b32 m0, s63
	s_nop 0
	global_load_lds_dwordx4 v130, s[0:1]
	s_cbranch_scc1 .LBB0_152
	s_barrier
